# gla_pass2: forward-direction chunk outputs kept in registers and exchanged through LDS in the backward chunks; the OF global round trip is gone
# speedup vs baseline: 1.0247x; 1.0114x over previous
; template <bool OUT>
; __device__ __forceinline__ void gla_chunks(const Params& p, int l, const bf16_t* proj, LAS unsigned char* lds, int seg, int h, int dir, f32x4 (&Sacc)[4], float* outbuf, float& alog) {
;     ...
;     const float* w2 = p.gw2 + ((size_t)(l * 2 + dir) * 16) * 256 + h * 64 + d; const float bias = p.gb[(l * 2 + dir) * 256 + h * 64 + d];
;     float w[16];
; #pragma unroll
;     for (int r = 0; r < 16; ++r) w[r] = w2[r * 256];
; __device__ void gla_pass2(const Params& p, int l, const bf16_t* proj, bf16_t* ycat, LAS unsigned char* lds) {
;     ...
;         for (int dir = 0; dir < 2; ++dir) {
;             f32x4 Sacc[4];
;             const size_t base = (size_t)(seg * 2 + dir) * 32768 + (size_t)h * 8192;
; #pragma unroll
;             for (int dt = 0; dt < 4; ++dt)
; #pragma unroll
;                 for (int r = 0; r < 4; ++r) Sacc[dt][r] = GS[base + (size_t)(dt * 16 + 4 * g + r) * 128 + 16 * wv + fr];
;             float alog = 0.f;
;             gla_chunks<true>(p, l, proj, lds, seg, h, dir, Sacc, dir ? OB : OF, alog);
.LBB0_434:
	s_or_b32 s6, s4, s61
	s_ashr_i32 s7, s6, 31
	s_lshl_b64 s[6:7], s[6:7], 17
	v_lshl_add_u64 v[4:5], v[80:81], 0, s[6:7]
	v_add_co_u32_e32 v6, vcc, 0x2000, v4
	s_movk_i32 s5, 0x4000
	s_nop 0
	v_addc_co_u32_e32 v7, vcc, 0, v5, vcc
	s_xor_b64 s[78:79], s[42:43], -1
	v_add_co_u32_e32 v12, vcc, s5, v4
	s_movk_i32 s5, 0x6000
	s_nop 0
	v_addc_co_u32_e32 v13, vcc, 0, v5, vcc
	s_and_b64 s[6:7], s[42:43], exec
	v_add_co_u32_e32 v16, vcc, s5, v4
	v_readlane_b32 s5, v253, 4
	v_readlane_b32 s6, v253, 6
	s_cselect_b32 s10, s5, s6
	v_readlane_b32 s5, v253, 3
	v_readlane_b32 s6, v253, 5
	s_cselect_b32 s11, s5, s6
	s_or_b32 s6, s4, s69
	s_ashr_i32 s7, s6, 31
	s_lshl_b64 s[8:9], s[6:7], 14
	v_addc_co_u32_e32 v17, vcc, 0, v5, vcc
	s_add_u32 s8, s73, s8
	global_load_dword v8, v[4:5], off
	global_load_dword v9, v[4:5], off offset:512
	global_load_dword v10, v[4:5], off offset:1024
	global_load_dword v11, v[4:5], off offset:1536
	global_load_dword v0, v[6:7], off
	global_load_dword v1, v[6:7], off offset:512
	global_load_dword v2, v[6:7], off offset:1024
	global_load_dword v3, v[6:7], off offset:1536
	s_nop 0
	global_load_dword v4, v[12:13], off
	global_load_dword v5, v[12:13], off offset:512
	global_load_dword v6, v[12:13], off offset:1024
	global_load_dword v7, v[12:13], off offset:1536
	s_nop 0
	global_load_dword v12, v[16:17], off
	global_load_dword v13, v[16:17], off offset:512
	global_load_dword v14, v[16:17], off offset:1024
	global_load_dword v15, v[16:17], off offset:1536
	v_mov_b32_e32 v17, v213
	s_addc_u32 s9, s62, s9
	s_lshl_b32 s5, s6, 8
	s_or_b32 s5, s5, s66
	v_and_b32_e32 v16, 63, v17
	v_or_b32_e32 v20, s5, v16
	v_readlane_b32 s16, v254, 48
	v_lshlrev_b32_e32 v188, 2, v16
	v_ashrrev_i32_e32 v21, 31, v20
	v_readlane_b32 s26, v254, 58
	v_readlane_b32 s27, v254, 59
	v_lshl_add_u64 v[18:19], s[8:9], 0, v[188:189]
	s_movk_i32 s5, 0x1000
	v_lshl_add_u64 v[20:21], v[20:21], 2, s[26:27]
	global_load_dword v91, v[20:21], off
	v_add_co_u32_e32 v20, vcc, s5, v18
	s_movk_i32 s5, 0x3000
	s_nop 0
	v_addc_co_u32_e32 v21, vcc, 0, v19, vcc
	v_add_co_u32_e32 v22, vcc, s92, v18
	v_readfirstlane_b32 s12, v17
	s_nop 0
	v_addc_co_u32_e32 v23, vcc, 0, v19, vcc
	v_add_co_u32_e32 v18, vcc, s5, v18
	s_nop 0
	s_nop 0
	s_nop 0
	s_nop 0
	s_nop 0
	s_nop 0
	s_nop 0
	s_nop 0
	v_addc_co_u32_e32 v19, vcc, 0, v19, vcc
	s_nop 0
	s_nop 0
	s_nop 0
	s_nop 0
	s_nop 0
	s_nop 0
	s_nop 0
	s_nop 0
	v_readlane_b32 s20, v254, 52
	s_lshl_b32 s50, s4, 4
	s_and_b32 s4, s12, 0x3fffffc0
	s_ashr_i32 s20, s12, 6
	s_lshl_b32 s4, s4, 2
	s_lshl_b32 s33, s20, 3
	s_add_i32 s4, s4, 0
	v_add_u32_e32 v108, s4, v188
	s_and_b64 s[4:5], s[42:43], exec
	v_readlane_b32 s28, v254, 60
	s_cselect_b32 s76, 1, -1
	s_cmp_lt_u32 s12, 64
	v_ashrrev_i32_e32 v18, 3, v17
	s_cselect_b64 s[80:81], -1, 0
	s_ashr_i32 s28, s12, 7
	v_and_b32_e32 v24, 15, v17
	v_bfe_u32 v19, v17, 4, 2
	v_and_b32_e32 v109, -2, v18
	v_lshlrev_b32_e32 v18, 3, v17
	v_add_u32_e32 v110, 0, v188
	s_movk_i32 s4, 0x8c
	s_lshl_b32 s6, s28, 4
	v_and_b32_e32 v17, 48, v17
	v_readlane_b32 s29, v254, 61
	v_mad_u32_u24 v20, v16, s4, v110
	s_lshl_b32 s4, s20, 1
	v_or_b32_e32 v21, s6, v24
	v_add_u32_e32 v82, 0, v17
	s_movk_i32 s7, 0x90
	s_and_b32 s29, s4, 2
	v_mad_u64_u32 v[84:85], s[4:5], v21, s7, v[82:83]
	s_lshl_b32 s40, s20, 4
	s_lshl_b32 s4, s28, 5
	v_lshlrev_b32_e32 v85, 2, v19
	s_add_i32 s4, s4, 0
	s_ashr_i32 s41, s40, 31
	v_lshlrev_b32_e32 v22, 3, v19
	v_or_b32_e32 v19, s6, v85
	v_or_b32_e32 v21, s40, v24
	s_add_u32 s6, s11, s67
	v_add_u32_e32 v111, s4, v22
	v_mul_lo_u32 v21, v21, s7
	s_addc_u32 s7, s10, 0
	s_lshl_b64 s[4:5], s[40:41], 2
	s_add_u32 s4, s6, s4
	s_addc_u32 s5, s7, s5
	s_or_b32 s77, s33, 1
	s_or_b32 s44, s33, 2
	s_or_b32 s45, s33, 3
	s_or_b32 s46, s33, 4
	s_or_b32 s47, s33, 5
	s_or_b32 s48, s33, 6
	s_or_b32 s49, s33, 7
	v_lshlrev_b32_e32 v188, 2, v24
	s_cmp_gt_i32 s20, 0
	v_lshl_add_u64 v[86:87], s[4:5], 0, v[188:189]
	s_cselect_b64 s[4:5], -1, 0
	s_cmp_gt_i32 s20, 1
	s_cselect_b64 s[6:7], -1, 0
	s_cmp_gt_i32 s20, 2
	s_cselect_b64 s[8:9], -1, 0
	s_cmp_gt_i32 s20, 3
	s_cselect_b64 s[10:11], -1, 0
	s_cmp_gt_i32 s20, 4
	s_cselect_b64 s[12:13], -1, 0
	s_cmp_gt_i32 s20, 5
	v_readlane_b32 s17, v254, 49
	v_and_b32_e32 v18, 0x78, v18
	s_cselect_b64 s[14:15], -1, 0
	s_cmp_gt_i32 s20, 6
	v_mul_u32_u24_e32 v23, 0x90, v18
	v_lshlrev_b32_e32 v25, 1, v109
	s_cselect_b64 s[16:17], -1, 0
	s_cmp_gt_i32 s20, 7
	s_mulk_i32 s20, 0x240
	v_readlane_b32 s18, v254, 50
	v_readlane_b32 s19, v254, 51
	v_readlane_b32 s21, v254, 53
	v_add3_u32 v112, 0, v23, v25
	v_or_b32_e32 v23, s20, v16
	s_mul_i32 s20, s44, 0x48
	s_cselect_b64 s[18:19], -1, 0
	v_lshl_add_u32 v113, v23, 1, 0
	v_add_u32_e32 v23, s20, v16
	s_add_i32 s21, s20, 0x90
	v_lshl_add_u32 v114, v23, 1, 0
	v_add_u32_e32 v23, s21, v16
	s_addk_i32 s20, 0x120
	v_lshl_add_u32 v115, v23, 1, 0
	v_add_u32_e32 v23, s20, v16
	s_cmp_ge_i32 s29, s28
	v_readlane_b32 s22, v254, 54
	v_readlane_b32 s23, v254, 55
	v_readlane_b32 s24, v254, 56
	v_readlane_b32 s25, v254, 57
	v_lshl_add_u32 v116, v23, 1, 0
	s_cselect_b64 s[82:83], -1, 0
	v_lshl_or_b32 v23, s29, 4, v24
	v_or_b32_e32 v25, 2, v19
	v_or_b32_e32 v26, 3, v19
	s_or_b32 s29, s29, 1
	v_readlane_b32 s30, v254, 62
	v_readlane_b32 s31, v254, 63
	v_mul_u32_u24_e32 v117, 0x90, v23
	v_cmp_gt_i32_e64 s[20:21], v19, v23
	v_cmp_lt_i32_e64 s[22:23], v19, v23
	v_cmp_gt_i32_e64 s[24:25], v25, v23
	v_cmp_gt_i32_e64 s[26:27], v26, v23
	v_lshl_or_b32 v23, s29, 4, v24
	v_add_u32_e32 v21, 0, v21
	v_sub_u32_e32 v22, v82, v22
	s_cmp_ge_i32 s29, s28
	v_cmp_gt_i32_e64 s[28:29], v19, v23
	v_cmp_lt_i32_e64 s[30:31], v19, v23
	v_mul_u32_u24_e32 v19, 0x90, v24
	s_mov_b32 s64, 3
	s_cselect_b64 s[84:85], -1, 0
	v_mul_u32_u24_e32 v118, 0x90, v23
	v_cmp_gt_i32_e64 s[34:35], v25, v23
	v_cmp_gt_i32_e64 s[36:37], v26, v23
	v_or_b32_e32 v119, 1, v85
	v_or_b32_e32 v120, 2, v85
	v_or_b32_e32 v121, 3, v85
	v_or_b32_e32 v122, 16, v85
	v_or_b32_e32 v123, 17, v85
	v_or_b32_e32 v124, 18, v85
	v_or_b32_e32 v125, 19, v85
	v_or_b32_e32 v126, 32, v85
	v_or_b32_e32 v127, 33, v85
	v_or_b32_e32 v128, 34, v85
	v_or_b32_e32 v129, 35, v85
	v_or_b32_e32 v130, 48, v85
	v_or_b32_e32 v131, 49, v85
	v_or_b32_e32 v132, 50, v85
	v_or_b32_e32 v133, 51, v85
	s_lshl_b32 s50, s50, 1
	v_lshlrev_b32_e32 v188, 1, v16
	v_lshlrev_b32_e32 v88, 1, v18
	v_add_u32_e32 v134, s40, v20
	v_add_u32_e32 v135, v21, v17
	v_add_u32_e32 v136, v82, v19
	v_add_u32_e32 v137, v22, v19
	s_mov_b32 s51, 0
	s_branch .LBB0_436
; #define LAS __attribute__((address_space(3)))
; template <bool OUT>
; __device__ __forceinline__ void gla_chunks(const Params& p, int l, const bf16_t* proj, LAS unsigned char* lds, int seg, int h, int dir, f32x4 (&Sacc)[4], float* outbuf, float& alog) {
;     ...
;             for (int it = 0; it < 4; ++it) { f32x4 o = {0.f, 0.f, 0.f, 0.f};
; #pragma unroll
;                 for (int ks = 0; ks < 2; ++ks) { const bf16x8 pf = *(const LAS bf16x8*)(PP + (it * 16 + fr) * GP + 32 * ks + 8 * g); o = __builtin_amdgcn_mfma_f32_16x16x32_bf16(pf, bv[ks], o, 0, 0, 0); }
; #pragma unroll
;                 for (int m = 0; m < 2; ++m) { const LAS bf16_t* qp = QT + (it * 16 + fr) * GP + 32 * m + 4 * g; const u32x2 lo = *(const LAS u32x2*)qp, hi = *(const LAS u32x2*)(qp + 16);
;                     u32x4 qw; qw.x = lo.x; qw.y = lo.y; qw.z = hi.x; qw.w = hi.y; o = __builtin_amdgcn_mfma_f32_16x16x32_bf16(__builtin_bit_cast(bf16x8, qw), bs[m], o, 0, 0, 0); }
; #pragma unroll
;                 for (int r = 0; r < 4; ++r) { const int i = it * 16 + 4 * g + r, t = dir ? t0 + 63 - i : t0 + i; outbuf[(size_t)t * 512 + h * 128 + 16 * wv + fr] = o[r]; } }
.Lp2b_435:
	v_mul_u32_u24_e32 v41, 0x210, v85
	v_lshl_add_u32 v41, v90, 6, v41
	v_and_b32_e32 v42, 15, v83
	v_lshl_add_u32 v41, v42, 2, v41
	v_add_u32_e32 v42, 0x16800, v41
	v_add_u32_e32 v41, 0xe400, v41
	s_cmp_eq_u32 s64, 1
	s_cbranch_scc1 .Lp2b_rs1
	s_cmp_eq_u32 s64, 2
	s_cbranch_scc1 .Lp2b_rs2
	s_cmp_eq_u32 s64, 3
	s_cbranch_scc1 .Lp2b_rs3
	ds_write_b32 v42, v48
	ds_write_b32 v42, v49 offset:528
	ds_write_b32 v42, v50 offset:1056
	ds_write_b32 v42, v51 offset:1584
	ds_write_b32 v42, v52 offset:8448
	ds_write_b32 v42, v53 offset:8976
	ds_write_b32 v42, v54 offset:9504
	ds_write_b32 v42, v55 offset:10032
	ds_write_b32 v42, v57 offset:16896
	ds_write_b32 v42, v58 offset:17424
	ds_write_b32 v42, v59 offset:17952
	ds_write_b32 v42, v60 offset:18480
	ds_write_b32 v42, v61 offset:25344
	ds_write_b32 v42, v62 offset:25872
	ds_write_b32 v42, v63 offset:26400
	ds_write_b32 v42, v65 offset:26928
	s_branch .Lp2b_rsdone
.Lp2b_rs1:
	ds_write_b32 v42, v66
	ds_write_b32 v42, v67 offset:528
	ds_write_b32 v42, v68 offset:1056
	ds_write_b32 v42, v69 offset:1584
	ds_write_b32 v42, v70 offset:8448
	ds_write_b32 v42, v71 offset:8976
	ds_write_b32 v42, v72 offset:9504
	ds_write_b32 v42, v73 offset:10032
	ds_write_b32 v42, v74 offset:16896
	ds_write_b32 v42, v75 offset:17424
	ds_write_b32 v42, v76 offset:17952
	ds_write_b32 v42, v77 offset:18480
	ds_write_b32 v42, v78 offset:25344
	ds_write_b32 v42, v79 offset:25872
	ds_write_b32 v42, v92 offset:26400
	ds_write_b32 v42, v93 offset:26928
	s_branch .Lp2b_rsdone
.Lp2b_rs2:
	ds_write_b32 v42, v94
	ds_write_b32 v42, v95 offset:528
	ds_write_b32 v42, v96 offset:1056
	ds_write_b32 v42, v97 offset:1584
	ds_write_b32 v42, v98 offset:8448
	ds_write_b32 v42, v99 offset:8976
	ds_write_b32 v42, v100 offset:9504
	ds_write_b32 v42, v101 offset:10032
	ds_write_b32 v42, v102 offset:16896
	ds_write_b32 v42, v103 offset:17424
	ds_write_b32 v42, v104 offset:17952
	ds_write_b32 v42, v105 offset:18480
	ds_write_b32 v42, v106 offset:25344
	ds_write_b32 v42, v107 offset:25872
	ds_write_b32 v42, v222 offset:26400
	ds_write_b32 v42, v223 offset:26928
	s_branch .Lp2b_rsdone
.Lp2b_rs3:
	ds_write_b32 v42, v224
	ds_write_b32 v42, v225 offset:528
	ds_write_b32 v42, v226 offset:1056
	ds_write_b32 v42, v227 offset:1584
	ds_write_b32 v42, v228 offset:8448
	ds_write_b32 v42, v229 offset:8976
	ds_write_b32 v42, v230 offset:9504
	ds_write_b32 v42, v231 offset:10032
	ds_write_b32 v42, v232 offset:16896
	ds_write_b32 v42, v233 offset:17424
	ds_write_b32 v42, v234 offset:17952
	ds_write_b32 v42, v235 offset:18480
	ds_write_b32 v42, v236 offset:25344
	ds_write_b32 v42, v237 offset:25872
	ds_write_b32 v42, v238 offset:26400
	ds_write_b32 v42, v239 offset:26928
.Lp2b_rsdone:
	v_cvt_pk_bf16_f32 v16, v22, v16
	v_cvt_pk_bf16_f32 v17, v17, v18
	s_nop 0
	v_add_u32_e32 v18, v111, v118
	ds_write_b64 v18, v[16:17] offset:46080
	s_waitcnt lgkmcnt(0)
	s_barrier
	ds_read_b128 v[20:23], v135 offset:27648
	ds_read_b128 v[16:19], v135 offset:27712
	ds_read_b128 v[156:159], v136 offset:46080
	ds_read_b128 v[160:163], v136 offset:46144
	ds_read2_b64 v[190:193], v137 offset1:4
	ds_read2_b64 v[194:197], v137 offset0:8 offset1:12
	ds_read_b128 v[164:167], v136 offset:48384
	ds_read_b128 v[168:171], v136 offset:48448
	v_add_u32_e32 v40, 0x800, v137
	ds_read2_b64 v[198:201], v40 offset0:32 offset1:36
	ds_read2_b64 v[202:205], v40 offset0:40 offset1:44
	ds_read_b128 v[172:175], v136 offset:50688
	ds_read_b128 v[176:179], v136 offset:50752
	ds_read_b128 v[180:183], v136 offset:52992
	ds_read_b128 v[184:187], v136 offset:53056
	v_cvt_pk_bf16_f32 v28, v8, v9
	v_cvt_pk_bf16_f32 v29, v10, v11
	v_cvt_pk_bf16_f32 v30, v0, v1
	v_cvt_pk_bf16_f32 v31, v2, v3
	v_cvt_pk_bf16_f32 v24, v4, v5
	v_cvt_pk_bf16_f32 v25, v6, v7
	v_cvt_pk_bf16_f32 v26, v12, v13
	v_cvt_pk_bf16_f32 v27, v14, v15
	s_waitcnt lgkmcnt(11)
	v_mfma_f32_16x16x32_bf16 v[32:35], v[156:159], v[20:23], 0
	s_waitcnt lgkmcnt(10)
	v_mfma_f32_16x16x32_bf16 v[32:35], v[160:163], v[16:19], v[32:35]
	s_waitcnt lgkmcnt(9)
	v_mfma_f32_16x16x32_bf16 v[32:35], v[190:193], v[28:31], v[32:35]
	s_waitcnt lgkmcnt(8)
	v_mfma_f32_16x16x32_bf16 v[32:35], v[194:197], v[24:27], v[32:35]
	v_add_u32_e32 v40, 0x1000, v137
	ds_read2_b64 v[138:141], v40 offset0:64 offset1:68
	ds_read2_b64 v[142:145], v40 offset0:72 offset1:76
	v_add_u32_e32 v40, 0x1800, v137
	ds_read2_b64 v[146:149], v40 offset0:96 offset1:100
	ds_read2_b64 v[150:153], v40 offset0:104 offset1:108
	s_waitcnt lgkmcnt(11)
	v_mfma_f32_16x16x32_bf16 v[36:39], v[164:167], v[20:23], 0
	s_waitcnt lgkmcnt(10)
	v_mfma_f32_16x16x32_bf16 v[36:39], v[168:171], v[16:19], v[36:39]
	s_waitcnt lgkmcnt(9)
	v_mfma_f32_16x16x32_bf16 v[36:39], v[198:201], v[28:31], v[36:39]
	s_waitcnt lgkmcnt(8)
	v_mfma_f32_16x16x32_bf16 v[36:39], v[202:205], v[24:27], v[36:39]
	ds_write_b32 v41, v32
	ds_write_b32 v41, v33 offset:528
	ds_write_b32 v41, v34 offset:1056
	ds_write_b32 v41, v35 offset:1584
	s_waitcnt lgkmcnt(7)
	v_mfma_f32_16x16x32_bf16 v[32:35], v[172:175], v[20:23], 0
	s_waitcnt lgkmcnt(6)
	v_mfma_f32_16x16x32_bf16 v[32:35], v[176:179], v[16:19], v[32:35]
	s_waitcnt lgkmcnt(3)
	v_mfma_f32_16x16x32_bf16 v[32:35], v[138:141], v[28:31], v[32:35]
	s_waitcnt lgkmcnt(2)
	v_mfma_f32_16x16x32_bf16 v[32:35], v[142:145], v[24:27], v[32:35]
	ds_write_b32 v41, v36 offset:8448
	ds_write_b32 v41, v37 offset:8976
	ds_write_b32 v41, v38 offset:9504
	ds_write_b32 v41, v39 offset:10032
	ds_read_b128 v[156:159], v82 offset:55296
	ds_read_b128 v[160:163], v82 offset:55360
	ds_read_b128 v[164:167], v82 offset:55424
	ds_read_b128 v[168:171], v82 offset:55488
	ds_read_b128 v[190:193], v136 offset:18432
	ds_read_b128 v[194:197], v136 offset:18496
	ds_read_b128 v[198:201], v136 offset:20736
	ds_read_b128 v[202:205], v136 offset:20800
	v_mfma_f32_16x16x32_bf16 v[36:39], v[180:183], v[20:23], 0
	v_mfma_f32_16x16x32_bf16 v[36:39], v[184:187], v[16:19], v[36:39]
	s_waitcnt lgkmcnt(9)
; __device__ void gla_pass2(const Params& p, int l, const bf16_t* proj, bf16_t* ycat, LAS unsigned char* lds) {
;     ...
;         for (int j0 = 0; j0 < 32; j0 += 8) {
;             f32x2 of[8], ob[8]; unsigned rw[8];
; #pragma unroll
;             for (int j = 0; j < 8; ++j) { const int t = seg * SEGLEN + wv * 32 + j0 + j; const size_t oo = (size_t)t * 512 + h * 128 + lane * 2;
;                 of[j] = *(const f32x2*)(OF + oo); ob[j] = *(const f32x2*)(OB + oo); rw[j] = *(const unsigned*)(proj + (size_t)t * NP + GR + h * 128 + lane * 2); }
; #pragma unroll
;             for (int j = 0; j < 8; ++j) { const int t = seg * SEGLEN + wv * 32 + j0 + j;
;                 const float o0 = of[j][0] + ob[j][0], o1 = of[j][1] + ob[j][1];
;                 const float ss = wave_sum(o0 * o0 + o1 * o1);
	v_mfma_f32_16x16x32_bf16 v[36:39], v[146:149], v[28:31], v[36:39]
	s_waitcnt lgkmcnt(8)
	v_mfma_f32_16x16x32_bf16 v[36:39], v[150:153], v[24:27], v[36:39]
	ds_read_b128 v[172:175], v136 offset:23040
	ds_read_b128 v[176:179], v136 offset:23104
	ds_read_b128 v[180:183], v136 offset:25344
	ds_read_b128 v[184:187], v136 offset:25408
	ds_write_b32 v41, v32 offset:16896
	ds_write_b32 v41, v33 offset:17424
	ds_write_b32 v41, v34 offset:17952
	ds_write_b32 v41, v35 offset:18480
	s_waitcnt lgkmcnt(8)
	v_pk_mul_f32 v[8:9], v[8:9], v[156:157]
	v_pk_mul_f32 v[10:11], v[10:11], v[158:159]
	v_pk_mul_f32 v[0:1], v[0:1], v[160:161]
	v_pk_mul_f32 v[2:3], v[2:3], v[162:163]
	v_pk_mul_f32 v[4:5], v[4:5], v[164:165]
	v_pk_mul_f32 v[6:7], v[6:7], v[166:167]
	v_pk_mul_f32 v[12:13], v[12:13], v[168:169]
	v_pk_mul_f32 v[14:15], v[14:15], v[170:171]
	ds_write_b32 v41, v36 offset:25344
	ds_write_b32 v41, v37 offset:25872
	ds_write_b32 v41, v38 offset:26400
	ds_write_b32 v41, v39 offset:26928
	s_waitcnt lgkmcnt(7)
	v_mfma_f32_16x16x32_bf16 v[8:11], v[190:193], v[20:23], v[8:11]
	s_waitcnt lgkmcnt(6)
	v_mfma_f32_16x16x32_bf16 v[8:11], v[194:197], v[16:19], v[8:11]
	s_waitcnt lgkmcnt(5)
	v_mfma_f32_16x16x32_bf16 v[0:3], v[198:201], v[20:23], v[0:3]
	s_waitcnt lgkmcnt(4)
	v_mfma_f32_16x16x32_bf16 v[0:3], v[202:205], v[16:19], v[0:3]
	s_waitcnt lgkmcnt(3)
	v_mfma_f32_16x16x32_bf16 v[4:7], v[172:175], v[20:23], v[4:7]
	s_waitcnt lgkmcnt(2)
	v_mfma_f32_16x16x32_bf16 v[4:7], v[176:179], v[16:19], v[4:7]
	s_waitcnt lgkmcnt(1)
	v_mfma_f32_16x16x32_bf16 v[12:15], v[180:183], v[20:23], v[12:15]
	s_waitcnt lgkmcnt(0)
	v_mfma_f32_16x16x32_bf16 v[12:15], v[184:187], v[16:19], v[12:15]
	s_add_i32 s51, s51, 1
	s_add_i32 s64, s64, -1
	s_cmp_lg_u32 s51, 4
	s_waitcnt lgkmcnt(0)
	s_barrier
	v_and_b32_e32 v166, 63, v83
	s_lshl_b32 s40, s66, 2
	v_lshlrev_b32_e32 v167, 2, v166
	v_add_u32_e32 v167, s40, v167
	v_lshl_add_u32 v168, v90, 13, v167
	v_mul_u32_u24_e32 v169, 0x1c000, v90
	v_add_u32_e32 v167, v169, v167
	v_lshlrev_b32_e32 v169, 3, v90
	v_sub_u32_e32 v170, 56, v169
	v_mul_u32_u24_e32 v170, 0x210, v170
	v_lshl_add_u32 v170, v166, 3, v170
	v_add_u32_e32 v170, 0xe400, v170
	v_mul_u32_u24_e32 v171, 0x210, v169
	v_lshl_add_u32 v171, v166, 3, v171
	v_add_u32_e32 v171, 0x16800, v171
	v_readlane_b32 s56, v255, 55
	v_readlane_b32 s57, v255, 56
	s_add_u32 s56, s56, s67
	s_addc_u32 s57, s57, 0
	v_lshlrev_b32_e32 v172, 3, v166
	s_nop 2
	global_load_dwordx2 v[156:157], v172, s[56:57]
	s_mul_i32 s40, s52, 0x3800
	s_add_u32 s40, s40, 0x20604200
	s_add_u32 s40, s86, s40
	s_addc_u32 s41, s87, 0
	global_load_dword v32, v167, s[40:41]
	s_add_u32 s40, s40, 0x3800
	s_addc_u32 s41, s41, 0
	global_load_dword v33, v167, s[40:41]
	s_add_u32 s40, s40, 0x3800
	s_addc_u32 s41, s41, 0
	global_load_dword v34, v167, s[40:41]
	s_add_u32 s40, s40, 0x3800
	s_addc_u32 s41, s41, 0
	global_load_dword v35, v167, s[40:41]
	s_add_u32 s40, s40, 0x3800
	s_addc_u32 s41, s41, 0
	global_load_dword v36, v167, s[40:41]
	s_add_u32 s40, s40, 0x3800
	s_addc_u32 s41, s41, 0
	global_load_dword v37, v167, s[40:41]
	s_add_u32 s40, s40, 0x3800
	s_addc_u32 s41, s41, 0
	global_load_dword v38, v167, s[40:41]
	s_add_u32 s40, s40, 0x3800
	s_addc_u32 s41, s41, 0
	global_load_dword v39, v167, s[40:41]
	ds_read_b64 v[138:139], v170 offset:3696
	ds_read_b64 v[140:141], v170 offset:3168
	ds_read_b64 v[142:143], v170 offset:2640
	ds_read_b64 v[144:145], v170 offset:2112
	ds_read_b64 v[146:147], v170 offset:1584
	ds_read_b64 v[148:149], v170 offset:1056
	ds_read_b64 v[150:151], v170 offset:528
	ds_read_b64 v[152:153], v170 offset:0
	ds_read_b64 v[16:17], v171
	ds_read_b64 v[18:19], v171 offset:528
	ds_read_b64 v[20:21], v171 offset:1056
	ds_read_b64 v[22:23], v171 offset:1584
	ds_read_b64 v[24:25], v171 offset:2112
	ds_read_b64 v[26:27], v171 offset:2640
	ds_read_b64 v[28:29], v171 offset:3168
	ds_read_b64 v[30:31], v171 offset:3696
	s_lshl_b32 s54, s52, 10
	s_add_u32 s54, s54, 0x30601000
	s_add_u32 s54, s86, s54
	s_addc_u32 s55, s87, 0
	s_add_u32 s56, s54, 0x1000
	s_addc_u32 s57, s55, 0
	s_waitcnt lgkmcnt(0)
	v_add_f32_e32 v16, v16, v138
	v_add_f32_e32 v17, v17, v139
	v_mul_f32_e32 v138, v16, v16
	v_mul_f32_e32 v139, v17, v17
	v_add_f32_e32 v138, v138, v139
	v_add_f32_e32 v18, v18, v140
	v_add_f32_e32 v19, v19, v141
	v_mul_f32_e32 v140, v18, v18
	v_mul_f32_e32 v141, v19, v19
	v_add_f32_e32 v140, v140, v141
	v_add_f32_e32 v20, v20, v142
	v_add_f32_e32 v21, v21, v143
	v_mul_f32_e32 v142, v20, v20
	v_mul_f32_e32 v143, v21, v21
	v_add_f32_e32 v142, v142, v143
	v_add_f32_e32 v22, v22, v144
	v_add_f32_e32 v23, v23, v145
	v_mul_f32_e32 v144, v22, v22
	v_mul_f32_e32 v145, v23, v23
	v_add_f32_e32 v144, v144, v145
	v_add_f32_e32 v24, v24, v146
	v_add_f32_e32 v25, v25, v147
	v_mul_f32_e32 v146, v24, v24
	v_mul_f32_e32 v147, v25, v25
	v_add_f32_e32 v146, v146, v147
	v_add_f32_e32 v26, v26, v148
	v_add_f32_e32 v27, v27, v149
	v_mul_f32_e32 v148, v26, v26
	v_mul_f32_e32 v149, v27, v27
	v_add_f32_e32 v148, v148, v149
	v_add_f32_e32 v28, v28, v150
	v_add_f32_e32 v29, v29, v151
	v_mul_f32_e32 v150, v28, v28
	v_mul_f32_e32 v151, v29, v29
	v_add_f32_e32 v150, v150, v151
	v_add_f32_e32 v30, v30, v152
	v_add_f32_e32 v31, v31, v153
	v_mul_f32_e32 v152, v30, v30
	v_mul_f32_e32 v153, v31, v31
	v_add_f32_e32 v152, v152, v153
	v_mov_b32_e32 v139, v138
	v_mov_b32_e32 v141, v140
	v_mov_b32_e32 v143, v142
	v_mov_b32_e32 v145, v144
	v_mov_b32_e32 v147, v146
	v_mov_b32_e32 v149, v148
	v_mov_b32_e32 v151, v150
	v_mov_b32_e32 v153, v152
	v_permlane32_swap_b32_e32 v139, v138
	v_permlane32_swap_b32_e32 v141, v140
	v_permlane32_swap_b32_e32 v143, v142
	v_permlane32_swap_b32_e32 v145, v144
; __device__ __forceinline__ unsigned cvt_pk_bf16(float lo, float hi) { unsigned r; asm("v_cvt_pk_bf16_f32 %0, %1, %2" : "=v"(r) : "v"(lo), "v"(hi)); return r; }
; __device__ __forceinline__ float bf_lo(unsigned w) { return __uint_as_float(w << 16); }
; __device__ __forceinline__ float bf_hi(unsigned w) { return __uint_as_float(w & 0xffff0000u); }
; __device__ void gla_pass2(const Params& p, int l, const bf16_t* proj, bf16_t* ycat, LAS unsigned char* lds) {
;     ...
;             for (int j = 0; j < 8; ++j) { const int t = seg * SEGLEN + wv * 32 + j0 + j;
;                 const float o0 = of[j][0] + ob[j][0], o1 = of[j][1] + ob[j][1];
;                 const float ss = wave_sum(o0 * o0 + o1 * o1);
;                 const float rs = rsqrtf(ss * (1.0f / 128.0f) + 1e-6f);
;                 const float r0 = bf_lo(rw[j]), r1 = bf_hi(rw[j]);
;                 const float y0 = o0 * rs * gg[0] * (r0 / (1.0f + __expf(-r0))), y1 = o1 * rs * gg[1] * (r1 / (1.0f + __expf(-r1)));
;                 *(unsigned*)(ycat + (size_t)2 * SEQ * 512 + (size_t)t * 512 + h * 128 + lane * 2) = cvt_pk_bf16(y0, y1); } }
	v_permlane32_swap_b32_e32 v147, v146
	v_permlane32_swap_b32_e32 v149, v148
	v_permlane32_swap_b32_e32 v151, v150
	v_permlane32_swap_b32_e32 v153, v152
	v_add_f32_e32 v138, v138, v139
	v_add_f32_e32 v140, v140, v141
	v_add_f32_e32 v142, v142, v143
	v_add_f32_e32 v144, v144, v145
	v_add_f32_e32 v146, v146, v147
	v_add_f32_e32 v148, v148, v149
	v_add_f32_e32 v150, v150, v151
	v_add_f32_e32 v152, v152, v153
	v_mov_b32_e32 v139, v138
	v_mov_b32_e32 v141, v140
	v_mov_b32_e32 v143, v142
	v_mov_b32_e32 v145, v144
	v_mov_b32_e32 v147, v146
	v_mov_b32_e32 v149, v148
	v_mov_b32_e32 v151, v150
	v_mov_b32_e32 v153, v152
	v_permlane16_swap_b32_e32 v139, v138
	v_permlane16_swap_b32_e32 v141, v140
	v_permlane16_swap_b32_e32 v143, v142
	v_permlane16_swap_b32_e32 v145, v144
	v_permlane16_swap_b32_e32 v147, v146
	v_permlane16_swap_b32_e32 v149, v148
	v_permlane16_swap_b32_e32 v151, v150
	v_permlane16_swap_b32_e32 v153, v152
	v_add_f32_e32 v138, v138, v139
	v_add_f32_e32 v140, v140, v141
	v_add_f32_e32 v142, v142, v143
	v_add_f32_e32 v144, v144, v145
	v_add_f32_e32 v146, v146, v147
	v_add_f32_e32 v148, v148, v149
	v_add_f32_e32 v150, v150, v151
	v_add_f32_e32 v152, v152, v153
	v_add_f32_dpp v138, v138, v138 row_ror:8 row_mask:0xf bank_mask:0xf
	v_add_f32_dpp v140, v140, v140 row_ror:8 row_mask:0xf bank_mask:0xf
	v_add_f32_dpp v142, v142, v142 row_ror:8 row_mask:0xf bank_mask:0xf
	v_add_f32_dpp v144, v144, v144 row_ror:8 row_mask:0xf bank_mask:0xf
	v_add_f32_dpp v146, v146, v146 row_ror:8 row_mask:0xf bank_mask:0xf
	v_add_f32_dpp v148, v148, v148 row_ror:8 row_mask:0xf bank_mask:0xf
	v_add_f32_dpp v150, v150, v150 row_ror:8 row_mask:0xf bank_mask:0xf
	v_add_f32_dpp v152, v152, v152 row_ror:8 row_mask:0xf bank_mask:0xf
	v_add_f32_dpp v138, v138, v138 row_ror:4 row_mask:0xf bank_mask:0xf
	v_add_f32_dpp v140, v140, v140 row_ror:4 row_mask:0xf bank_mask:0xf
	v_add_f32_dpp v142, v142, v142 row_ror:4 row_mask:0xf bank_mask:0xf
	v_add_f32_dpp v144, v144, v144 row_ror:4 row_mask:0xf bank_mask:0xf
	v_add_f32_dpp v146, v146, v146 row_ror:4 row_mask:0xf bank_mask:0xf
	v_add_f32_dpp v148, v148, v148 row_ror:4 row_mask:0xf bank_mask:0xf
	v_add_f32_dpp v150, v150, v150 row_ror:4 row_mask:0xf bank_mask:0xf
	v_add_f32_dpp v152, v152, v152 row_ror:4 row_mask:0xf bank_mask:0xf
	v_add_f32_dpp v138, v138, v138 quad_perm:[2,3,0,1] row_mask:0xf bank_mask:0xf
	v_add_f32_dpp v140, v140, v140 quad_perm:[2,3,0,1] row_mask:0xf bank_mask:0xf
	v_add_f32_dpp v142, v142, v142 quad_perm:[2,3,0,1] row_mask:0xf bank_mask:0xf
	v_add_f32_dpp v144, v144, v144 quad_perm:[2,3,0,1] row_mask:0xf bank_mask:0xf
	v_add_f32_dpp v146, v146, v146 quad_perm:[2,3,0,1] row_mask:0xf bank_mask:0xf
	v_add_f32_dpp v148, v148, v148 quad_perm:[2,3,0,1] row_mask:0xf bank_mask:0xf
	v_add_f32_dpp v150, v150, v150 quad_perm:[2,3,0,1] row_mask:0xf bank_mask:0xf
	v_add_f32_dpp v152, v152, v152 quad_perm:[2,3,0,1] row_mask:0xf bank_mask:0xf
	v_add_f32_dpp v138, v138, v138 quad_perm:[1,0,3,2] row_mask:0xf bank_mask:0xf
	v_add_f32_dpp v140, v140, v140 quad_perm:[1,0,3,2] row_mask:0xf bank_mask:0xf
	v_add_f32_dpp v142, v142, v142 quad_perm:[1,0,3,2] row_mask:0xf bank_mask:0xf
	v_add_f32_dpp v144, v144, v144 quad_perm:[1,0,3,2] row_mask:0xf bank_mask:0xf
	v_add_f32_dpp v146, v146, v146 quad_perm:[1,0,3,2] row_mask:0xf bank_mask:0xf
	v_add_f32_dpp v148, v148, v148 quad_perm:[1,0,3,2] row_mask:0xf bank_mask:0xf
	v_add_f32_dpp v150, v150, v150 quad_perm:[1,0,3,2] row_mask:0xf bank_mask:0xf
	v_add_f32_dpp v152, v152, v152 quad_perm:[1,0,3,2] row_mask:0xf bank_mask:0xf
	s_waitcnt vmcnt(0)
	v_fmamk_f32 v138, v138, 0x3c000000, v212
	v_cmp_gt_f32_e32 vcc, s1, v138
	v_mul_f32_e32 v174, 0x4b800000, v138
	v_lshlrev_b32_e32 v175, 16, v32
	v_cndmask_b32_e32 v138, v138, v174, vcc
	v_rsq_f32_e32 v138, v138
	v_and_b32_e32 v176, 0xffff0000, v32
	v_mul_f32_e32 v174, 0x45800000, v138
	v_mul_f32_e32 v177, 0xbfb8aa3b, v175
	v_cndmask_b32_e32 v138, v138, v174, vcc
	v_exp_f32_e32 v177, v177
	v_mul_f32_e32 v178, 0xbfb8aa3b, v176
	v_exp_f32_e32 v178, v178
	v_mul_f32_e32 v16, v16, v138
	v_mul_f32_e32 v17, v17, v138
	v_add_f32_e32 v177, 1.0, v177
	v_add_f32_e32 v178, 1.0, v178
	v_mul_f32_e32 v16, v156, v16
	v_mul_f32_e32 v17, v157, v17
	v_div_scale_f32 v179, s[40:41], v177, v177, v175
	v_div_scale_f32 v180, s[40:41], v178, v178, v176
	v_rcp_f32_e32 v181, v179
	v_rcp_f32_e32 v182, v180
	v_fma_f32 v183, -v179, v181, 1.0
	v_fma_f32 v184, -v180, v182, 1.0
	v_fmac_f32_e32 v181, v183, v181
	v_fmac_f32_e32 v182, v184, v182
	v_div_scale_f32 v183, vcc, v175, v177, v175
	v_mul_f32_e32 v185, v183, v181
	v_fma_f32 v187, -v179, v185, v183
	v_fmac_f32_e32 v185, v187, v181
	v_fma_f32 v179, -v179, v185, v183
	v_div_fmas_f32 v179, v179, v181, v185
	v_div_fixup_f32 v175, v179, v177, v175
	v_div_scale_f32 v184, vcc, v176, v178, v176
	v_mul_f32_e32 v186, v184, v182
	v_fma_f32 v187, -v180, v186, v184
	v_fmac_f32_e32 v186, v187, v182
	v_fma_f32 v180, -v180, v186, v184
	v_div_fmas_f32 v180, v180, v182, v186
	v_div_fixup_f32 v176, v180, v178, v176
	v_mul_f32_e32 v16, v175, v16
	v_mul_f32_e32 v17, v176, v17
	v_cvt_pk_bf16_f32 v158, v16, v17
	global_store_dword v168, v158, s[54:55]
	v_fmamk_f32 v140, v140, 0x3c000000, v212
	v_cmp_gt_f32_e32 vcc, s1, v140
	v_mul_f32_e32 v174, 0x4b800000, v140
	v_lshlrev_b32_e32 v175, 16, v33
	v_cndmask_b32_e32 v140, v140, v174, vcc
	v_rsq_f32_e32 v140, v140
	v_and_b32_e32 v176, 0xffff0000, v33
	v_mul_f32_e32 v174, 0x45800000, v140
	v_mul_f32_e32 v177, 0xbfb8aa3b, v175
	v_cndmask_b32_e32 v140, v140, v174, vcc
	v_exp_f32_e32 v177, v177
	v_mul_f32_e32 v178, 0xbfb8aa3b, v176
	v_exp_f32_e32 v178, v178
	v_mul_f32_e32 v18, v18, v140
; __device__ __forceinline__ unsigned cvt_pk_bf16(float lo, float hi) { unsigned r; asm("v_cvt_pk_bf16_f32 %0, %1, %2" : "=v"(r) : "v"(lo), "v"(hi)); return r; }
; __device__ __forceinline__ float bf_lo(unsigned w) { return __uint_as_float(w << 16); }
; __device__ __forceinline__ float bf_hi(unsigned w) { return __uint_as_float(w & 0xffff0000u); }
; __device__ void gla_pass2(const Params& p, int l, const bf16_t* proj, bf16_t* ycat, LAS unsigned char* lds) {
;     ...
;             for (int j = 0; j < 8; ++j) { const int t = seg * SEGLEN + wv * 32 + j0 + j;
;                 const float o0 = of[j][0] + ob[j][0], o1 = of[j][1] + ob[j][1];
;                 const float ss = wave_sum(o0 * o0 + o1 * o1);
;                 const float rs = rsqrtf(ss * (1.0f / 128.0f) + 1e-6f);
;                 const float r0 = bf_lo(rw[j]), r1 = bf_hi(rw[j]);
;                 const float y0 = o0 * rs * gg[0] * (r0 / (1.0f + __expf(-r0))), y1 = o1 * rs * gg[1] * (r1 / (1.0f + __expf(-r1)));
;                 *(unsigned*)(ycat + (size_t)2 * SEQ * 512 + (size_t)t * 512 + h * 128 + lane * 2) = cvt_pk_bf16(y0, y1); } }
	v_mul_f32_e32 v19, v19, v140
	v_add_f32_e32 v177, 1.0, v177
	v_add_f32_e32 v178, 1.0, v178
	v_mul_f32_e32 v18, v156, v18
	v_mul_f32_e32 v19, v157, v19
	v_div_scale_f32 v179, s[40:41], v177, v177, v175
	v_div_scale_f32 v180, s[40:41], v178, v178, v176
	v_rcp_f32_e32 v181, v179
	v_rcp_f32_e32 v182, v180
	v_fma_f32 v183, -v179, v181, 1.0
	v_fma_f32 v184, -v180, v182, 1.0
	v_fmac_f32_e32 v181, v183, v181
	v_fmac_f32_e32 v182, v184, v182
	v_div_scale_f32 v183, vcc, v175, v177, v175
	v_mul_f32_e32 v185, v183, v181
	v_fma_f32 v187, -v179, v185, v183
	v_fmac_f32_e32 v185, v187, v181
	v_fma_f32 v179, -v179, v185, v183
	v_div_fmas_f32 v179, v179, v181, v185
	v_div_fixup_f32 v175, v179, v177, v175
	v_div_scale_f32 v184, vcc, v176, v178, v176
	v_mul_f32_e32 v186, v184, v182
	v_fma_f32 v187, -v180, v186, v184
	v_fmac_f32_e32 v186, v187, v182
	v_fma_f32 v180, -v180, v186, v184
	v_div_fmas_f32 v180, v180, v182, v186
	v_div_fixup_f32 v176, v180, v178, v176
	v_mul_f32_e32 v18, v175, v18
	v_mul_f32_e32 v19, v176, v19
	v_cvt_pk_bf16_f32 v159, v18, v19
	global_store_dword v168, v159, s[54:55] offset:1024
	v_fmamk_f32 v142, v142, 0x3c000000, v212
	v_cmp_gt_f32_e32 vcc, s1, v142
	v_mul_f32_e32 v174, 0x4b800000, v142
	v_lshlrev_b32_e32 v175, 16, v34
	v_cndmask_b32_e32 v142, v142, v174, vcc
	v_rsq_f32_e32 v142, v142
	v_and_b32_e32 v176, 0xffff0000, v34
	v_mul_f32_e32 v174, 0x45800000, v142
	v_mul_f32_e32 v177, 0xbfb8aa3b, v175
	v_cndmask_b32_e32 v142, v142, v174, vcc
	v_exp_f32_e32 v177, v177
	v_mul_f32_e32 v178, 0xbfb8aa3b, v176
	v_exp_f32_e32 v178, v178
	v_mul_f32_e32 v20, v20, v142
	v_mul_f32_e32 v21, v21, v142
	v_add_f32_e32 v177, 1.0, v177
	v_add_f32_e32 v178, 1.0, v178
	v_mul_f32_e32 v20, v156, v20
	v_mul_f32_e32 v21, v157, v21
	v_div_scale_f32 v179, s[40:41], v177, v177, v175
	v_div_scale_f32 v180, s[40:41], v178, v178, v176
	v_rcp_f32_e32 v181, v179
	v_rcp_f32_e32 v182, v180
	v_fma_f32 v183, -v179, v181, 1.0
	v_fma_f32 v184, -v180, v182, 1.0
	v_fmac_f32_e32 v181, v183, v181
	v_fmac_f32_e32 v182, v184, v182
	v_div_scale_f32 v183, vcc, v175, v177, v175
	v_mul_f32_e32 v185, v183, v181
	v_fma_f32 v187, -v179, v185, v183
	v_fmac_f32_e32 v185, v187, v181
	v_fma_f32 v179, -v179, v185, v183
	v_div_fmas_f32 v179, v179, v181, v185
	v_div_fixup_f32 v175, v179, v177, v175
	v_div_scale_f32 v184, vcc, v176, v178, v176
	v_mul_f32_e32 v186, v184, v182
	v_fma_f32 v187, -v180, v186, v184
	v_fmac_f32_e32 v186, v187, v182
	v_fma_f32 v180, -v180, v186, v184
	v_div_fmas_f32 v180, v180, v182, v186
	v_div_fixup_f32 v176, v180, v178, v176
	v_mul_f32_e32 v20, v175, v20
	v_mul_f32_e32 v21, v176, v21
	v_cvt_pk_bf16_f32 v160, v20, v21
	global_store_dword v168, v160, s[54:55] offset:2048
	v_fmamk_f32 v144, v144, 0x3c000000, v212
	v_cmp_gt_f32_e32 vcc, s1, v144
	v_mul_f32_e32 v174, 0x4b800000, v144
	v_lshlrev_b32_e32 v175, 16, v35
	v_cndmask_b32_e32 v144, v144, v174, vcc
	v_rsq_f32_e32 v144, v144
	v_and_b32_e32 v176, 0xffff0000, v35
	v_mul_f32_e32 v174, 0x45800000, v144
	v_mul_f32_e32 v177, 0xbfb8aa3b, v175
	v_cndmask_b32_e32 v144, v144, v174, vcc
	v_exp_f32_e32 v177, v177
	v_mul_f32_e32 v178, 0xbfb8aa3b, v176
	v_exp_f32_e32 v178, v178
	v_mul_f32_e32 v22, v22, v144
	v_mul_f32_e32 v23, v23, v144
	v_add_f32_e32 v177, 1.0, v177
	v_add_f32_e32 v178, 1.0, v178
	v_mul_f32_e32 v22, v156, v22
	v_mul_f32_e32 v23, v157, v23
	v_div_scale_f32 v179, s[40:41], v177, v177, v175
	v_div_scale_f32 v180, s[40:41], v178, v178, v176
	v_rcp_f32_e32 v181, v179
	v_rcp_f32_e32 v182, v180
	v_fma_f32 v183, -v179, v181, 1.0
	v_fma_f32 v184, -v180, v182, 1.0
	v_fmac_f32_e32 v181, v183, v181
	v_fmac_f32_e32 v182, v184, v182
	v_div_scale_f32 v183, vcc, v175, v177, v175
	v_mul_f32_e32 v185, v183, v181
	v_fma_f32 v187, -v179, v185, v183
	v_fmac_f32_e32 v185, v187, v181
	v_fma_f32 v179, -v179, v185, v183
	v_div_fmas_f32 v179, v179, v181, v185
	v_div_fixup_f32 v175, v179, v177, v175
	v_div_scale_f32 v184, vcc, v176, v178, v176
	v_mul_f32_e32 v186, v184, v182
	v_fma_f32 v187, -v180, v186, v184
	v_fmac_f32_e32 v186, v187, v182
	v_fma_f32 v180, -v180, v186, v184
	v_div_fmas_f32 v180, v180, v182, v186
	v_div_fixup_f32 v176, v180, v178, v176
	v_mul_f32_e32 v22, v175, v22
	v_mul_f32_e32 v23, v176, v23
	v_cvt_pk_bf16_f32 v161, v22, v23
	global_store_dword v168, v161, s[54:55] offset:3072
	v_fmamk_f32 v146, v146, 0x3c000000, v212
	v_cmp_gt_f32_e32 vcc, s1, v146
	v_mul_f32_e32 v174, 0x4b800000, v146
	v_lshlrev_b32_e32 v175, 16, v36
	v_cndmask_b32_e32 v146, v146, v174, vcc
	v_rsq_f32_e32 v146, v146
	v_and_b32_e32 v176, 0xffff0000, v36
	v_mul_f32_e32 v174, 0x45800000, v146
	v_mul_f32_e32 v177, 0xbfb8aa3b, v175
	v_cndmask_b32_e32 v146, v146, v174, vcc
	v_exp_f32_e32 v177, v177
	v_mul_f32_e32 v178, 0xbfb8aa3b, v176
	v_exp_f32_e32 v178, v178
	v_mul_f32_e32 v24, v24, v146
	v_mul_f32_e32 v25, v25, v146
	v_add_f32_e32 v177, 1.0, v177
	v_add_f32_e32 v178, 1.0, v178
	v_mul_f32_e32 v24, v156, v24
	v_mul_f32_e32 v25, v157, v25
	v_div_scale_f32 v179, s[40:41], v177, v177, v175
	v_div_scale_f32 v180, s[40:41], v178, v178, v176
	v_rcp_f32_e32 v181, v179
	v_rcp_f32_e32 v182, v180
	v_fma_f32 v183, -v179, v181, 1.0
	v_fma_f32 v184, -v180, v182, 1.0
	v_fmac_f32_e32 v181, v183, v181
	v_fmac_f32_e32 v182, v184, v182
	v_div_scale_f32 v183, vcc, v175, v177, v175
	v_mul_f32_e32 v185, v183, v181
	v_fma_f32 v187, -v179, v185, v183
	v_fmac_f32_e32 v185, v187, v181
	v_fma_f32 v179, -v179, v185, v183
	v_div_fmas_f32 v179, v179, v181, v185
	v_div_fixup_f32 v175, v179, v177, v175
	v_div_scale_f32 v184, vcc, v176, v178, v176
	v_mul_f32_e32 v186, v184, v182
	v_fma_f32 v187, -v180, v186, v184
	v_fmac_f32_e32 v186, v187, v182
	v_fma_f32 v180, -v180, v186, v184
; __device__ __forceinline__ unsigned cvt_pk_bf16(float lo, float hi) { unsigned r; asm("v_cvt_pk_bf16_f32 %0, %1, %2" : "=v"(r) : "v"(lo), "v"(hi)); return r; }
; __device__ __forceinline__ float bf_lo(unsigned w) { return __uint_as_float(w << 16); }
; __device__ __forceinline__ float bf_hi(unsigned w) { return __uint_as_float(w & 0xffff0000u); }
; __device__ void gla_pass2(const Params& p, int l, const bf16_t* proj, bf16_t* ycat, LAS unsigned char* lds) {
;     ...
;             for (int j = 0; j < 8; ++j) { const int t = seg * SEGLEN + wv * 32 + j0 + j;
;                 const float o0 = of[j][0] + ob[j][0], o1 = of[j][1] + ob[j][1];
;                 const float ss = wave_sum(o0 * o0 + o1 * o1);
;                 const float rs = rsqrtf(ss * (1.0f / 128.0f) + 1e-6f);
;                 const float r0 = bf_lo(rw[j]), r1 = bf_hi(rw[j]);
;                 const float y0 = o0 * rs * gg[0] * (r0 / (1.0f + __expf(-r0))), y1 = o1 * rs * gg[1] * (r1 / (1.0f + __expf(-r1)));
;                 *(unsigned*)(ycat + (size_t)2 * SEQ * 512 + (size_t)t * 512 + h * 128 + lane * 2) = cvt_pk_bf16(y0, y1); } }
	v_div_fmas_f32 v180, v180, v182, v186
	v_div_fixup_f32 v176, v180, v178, v176
	v_mul_f32_e32 v24, v175, v24
	v_mul_f32_e32 v25, v176, v25
	v_cvt_pk_bf16_f32 v162, v24, v25
	global_store_dword v168, v162, s[56:57]
	v_fmamk_f32 v148, v148, 0x3c000000, v212
	v_cmp_gt_f32_e32 vcc, s1, v148
	v_mul_f32_e32 v174, 0x4b800000, v148
	v_lshlrev_b32_e32 v175, 16, v37
	v_cndmask_b32_e32 v148, v148, v174, vcc
	v_rsq_f32_e32 v148, v148
	v_and_b32_e32 v176, 0xffff0000, v37
	v_mul_f32_e32 v174, 0x45800000, v148
	v_mul_f32_e32 v177, 0xbfb8aa3b, v175
	v_cndmask_b32_e32 v148, v148, v174, vcc
	v_exp_f32_e32 v177, v177
	v_mul_f32_e32 v178, 0xbfb8aa3b, v176
	v_exp_f32_e32 v178, v178
	v_mul_f32_e32 v26, v26, v148
	v_mul_f32_e32 v27, v27, v148
	v_add_f32_e32 v177, 1.0, v177
	v_add_f32_e32 v178, 1.0, v178
	v_mul_f32_e32 v26, v156, v26
	v_mul_f32_e32 v27, v157, v27
	v_div_scale_f32 v179, s[40:41], v177, v177, v175
	v_div_scale_f32 v180, s[40:41], v178, v178, v176
	v_rcp_f32_e32 v181, v179
	v_rcp_f32_e32 v182, v180
	v_fma_f32 v183, -v179, v181, 1.0
	v_fma_f32 v184, -v180, v182, 1.0
	v_fmac_f32_e32 v181, v183, v181
	v_fmac_f32_e32 v182, v184, v182
	v_div_scale_f32 v183, vcc, v175, v177, v175
	v_mul_f32_e32 v185, v183, v181
	v_fma_f32 v187, -v179, v185, v183
	v_fmac_f32_e32 v185, v187, v181
	v_fma_f32 v179, -v179, v185, v183
	v_div_fmas_f32 v179, v179, v181, v185
	v_div_fixup_f32 v175, v179, v177, v175
	v_div_scale_f32 v184, vcc, v176, v178, v176
	v_mul_f32_e32 v186, v184, v182
	v_fma_f32 v187, -v180, v186, v184
	v_fmac_f32_e32 v186, v187, v182
	v_fma_f32 v180, -v180, v186, v184
	v_div_fmas_f32 v180, v180, v182, v186
	v_div_fixup_f32 v176, v180, v178, v176
	v_mul_f32_e32 v26, v175, v26
	v_mul_f32_e32 v27, v176, v27
	v_cvt_pk_bf16_f32 v163, v26, v27
	global_store_dword v168, v163, s[56:57] offset:1024
	v_fmamk_f32 v150, v150, 0x3c000000, v212
	v_cmp_gt_f32_e32 vcc, s1, v150
	v_mul_f32_e32 v174, 0x4b800000, v150
	v_lshlrev_b32_e32 v175, 16, v38
	v_cndmask_b32_e32 v150, v150, v174, vcc
	v_rsq_f32_e32 v150, v150
	v_and_b32_e32 v176, 0xffff0000, v38
	v_mul_f32_e32 v174, 0x45800000, v150
	v_mul_f32_e32 v177, 0xbfb8aa3b, v175
	v_cndmask_b32_e32 v150, v150, v174, vcc
	v_exp_f32_e32 v177, v177
	v_mul_f32_e32 v178, 0xbfb8aa3b, v176
	v_exp_f32_e32 v178, v178
	v_mul_f32_e32 v28, v28, v150
	v_mul_f32_e32 v29, v29, v150
	v_add_f32_e32 v177, 1.0, v177
	v_add_f32_e32 v178, 1.0, v178
	v_mul_f32_e32 v28, v156, v28
	v_mul_f32_e32 v29, v157, v29
	v_div_scale_f32 v179, s[40:41], v177, v177, v175
	v_div_scale_f32 v180, s[40:41], v178, v178, v176
	v_rcp_f32_e32 v181, v179
	v_rcp_f32_e32 v182, v180
	v_fma_f32 v183, -v179, v181, 1.0
	v_fma_f32 v184, -v180, v182, 1.0
	v_fmac_f32_e32 v181, v183, v181
	v_fmac_f32_e32 v182, v184, v182
	v_div_scale_f32 v183, vcc, v175, v177, v175
	v_mul_f32_e32 v185, v183, v181
	v_fma_f32 v187, -v179, v185, v183
	v_fmac_f32_e32 v185, v187, v181
	v_fma_f32 v179, -v179, v185, v183
	v_div_fmas_f32 v179, v179, v181, v185
	v_div_fixup_f32 v175, v179, v177, v175
	v_div_scale_f32 v184, vcc, v176, v178, v176
	v_mul_f32_e32 v186, v184, v182
	v_fma_f32 v187, -v180, v186, v184
	v_fmac_f32_e32 v186, v187, v182
	v_fma_f32 v180, -v180, v186, v184
	v_div_fmas_f32 v180, v180, v182, v186
	v_div_fixup_f32 v176, v180, v178, v176
	v_mul_f32_e32 v28, v175, v28
	v_mul_f32_e32 v29, v176, v29
	v_cvt_pk_bf16_f32 v164, v28, v29
	global_store_dword v168, v164, s[56:57] offset:2048
	v_fmamk_f32 v152, v152, 0x3c000000, v212
	v_cmp_gt_f32_e32 vcc, s1, v152
	v_mul_f32_e32 v174, 0x4b800000, v152
	v_lshlrev_b32_e32 v175, 16, v39
	v_cndmask_b32_e32 v152, v152, v174, vcc
	v_rsq_f32_e32 v152, v152
	v_and_b32_e32 v176, 0xffff0000, v39
	v_mul_f32_e32 v174, 0x45800000, v152
	v_mul_f32_e32 v177, 0xbfb8aa3b, v175
	v_cndmask_b32_e32 v152, v152, v174, vcc
	v_exp_f32_e32 v177, v177
	v_mul_f32_e32 v178, 0xbfb8aa3b, v176
	v_exp_f32_e32 v178, v178
	v_mul_f32_e32 v30, v30, v152
	v_mul_f32_e32 v31, v31, v152
	v_add_f32_e32 v177, 1.0, v177
	v_add_f32_e32 v178, 1.0, v178
	v_mul_f32_e32 v30, v156, v30
	v_mul_f32_e32 v31, v157, v31
	v_div_scale_f32 v179, s[40:41], v177, v177, v175
	v_div_scale_f32 v180, s[40:41], v178, v178, v176
	v_rcp_f32_e32 v181, v179
	v_rcp_f32_e32 v182, v180
	v_fma_f32 v183, -v179, v181, 1.0
	v_fma_f32 v184, -v180, v182, 1.0
	v_fmac_f32_e32 v181, v183, v181
	v_fmac_f32_e32 v182, v184, v182
	v_div_scale_f32 v183, vcc, v175, v177, v175
	v_mul_f32_e32 v185, v183, v181
	v_fma_f32 v187, -v179, v185, v183
	v_fmac_f32_e32 v185, v187, v181
	v_fma_f32 v179, -v179, v185, v183
	v_div_fmas_f32 v179, v179, v181, v185
	v_div_fixup_f32 v175, v179, v177, v175
	v_div_scale_f32 v184, vcc, v176, v178, v176
	v_mul_f32_e32 v186, v184, v182
	v_fma_f32 v187, -v180, v186, v184
	v_fmac_f32_e32 v186, v187, v182
	v_fma_f32 v180, -v180, v186, v184
	v_div_fmas_f32 v180, v180, v182, v186
	v_div_fixup_f32 v176, v180, v178, v176
	v_mul_f32_e32 v30, v175, v30
	v_mul_f32_e32 v31, v176, v31
	v_cvt_pk_bf16_f32 v165, v30, v31
	global_store_dword v168, v165, s[56:57] offset:3072
	s_cmp_lg_u32 s51, 4
	s_cbranch_scc0 .LBB0_433
	s_branch .LBB0_436
; #define LAS __attribute__((address_space(3)))
; template <bool OUT>
; __device__ __forceinline__ void gla_chunks(const Params& p, int l, const bf16_t* proj, LAS unsigned char* lds, int seg, int h, int dir, f32x4 (&Sacc)[4], float* outbuf, float& alog) {
;     ...
;             for (int it = 0; it < 4; ++it) { f32x4 o = {0.f, 0.f, 0.f, 0.f};
; #pragma unroll
;                 for (int ks = 0; ks < 2; ++ks) { const bf16x8 pf = *(const LAS bf16x8*)(PP + (it * 16 + fr) * GP + 32 * ks + 8 * g); o = __builtin_amdgcn_mfma_f32_16x16x32_bf16(pf, bv[ks], o, 0, 0, 0); }
; #pragma unroll
;                 for (int m = 0; m < 2; ++m) { const LAS bf16_t* qp = QT + (it * 16 + fr) * GP + 32 * m + 4 * g; const u32x2 lo = *(const LAS u32x2*)qp, hi = *(const LAS u32x2*)(qp + 16);
;                     u32x4 qw; qw.x = lo.x; qw.y = lo.y; qw.z = hi.x; qw.w = hi.y; o = __builtin_amdgcn_mfma_f32_16x16x32_bf16(__builtin_bit_cast(bf16x8, qw), bs[m], o, 0, 0, 0); }
; #pragma unroll
;                 for (int r = 0; r < 4; ++r) { const int i = it * 16 + 4 * g + r, t = dir ? t0 + 63 - i : t0 + i; outbuf[(size_t)t * 512 + h * 128 + 16 * wv + fr] = o[r]; } }
;         }
; #pragma unroll
;         for (int dt = 0; dt < 4; ++dt) { const f32x4 eb = *(const LAS f32x4*)(EBL + dt * 16 + 4 * g); f32x4 a = Sacc[dt] * eb;
; #pragma unroll
;             for (int ks = 0; ks < 2; ++ks) { const bf16x8 kf = *(const LAS bf16x8*)(KH + (dt * 16 + fr) * GP + 32 * ks + 8 * g); a = __builtin_amdgcn_mfma_f32_16x16x32_bf16(kf, bv[ks], a, 0, 0, 0); }
;             Sacc[dt] = a; }
.LBB0_435:
	s_and_b64 s[40:41], s[42:43], exec
	s_cbranch_scc0 .Lp2b_435
	v_cvt_pk_bf16_f32 v16, v22, v16
	v_cvt_pk_bf16_f32 v17, v17, v18
	s_nop 0
	v_add_u32_e32 v18, v111, v118
	ds_write_b64 v18, v[16:17] offset:46080
	s_waitcnt lgkmcnt(0)
	s_barrier
	ds_read_b128 v[20:23], v135 offset:27648
	ds_read_b128 v[16:19], v135 offset:27712
	ds_read_b128 v[156:159], v136 offset:46080
	ds_read_b128 v[160:163], v136 offset:46144
	ds_read2_b64 v[190:193], v137 offset1:4
	ds_read2_b64 v[194:197], v137 offset0:8 offset1:12
	ds_read_b128 v[164:167], v136 offset:48384
	ds_read_b128 v[168:171], v136 offset:48448
	v_add_u32_e32 v40, 0x800, v137
	ds_read2_b64 v[198:201], v40 offset0:32 offset1:36
	ds_read2_b64 v[202:205], v40 offset0:40 offset1:44
	ds_read_b128 v[172:175], v136 offset:50688
	ds_read_b128 v[176:179], v136 offset:50752
	ds_read_b128 v[180:183], v136 offset:52992
	ds_read_b128 v[184:187], v136 offset:53056
	v_cvt_pk_bf16_f32 v28, v8, v9
	v_cvt_pk_bf16_f32 v29, v10, v11
	v_cvt_pk_bf16_f32 v30, v0, v1
	v_cvt_pk_bf16_f32 v31, v2, v3
	v_cvt_pk_bf16_f32 v24, v4, v5
	v_cvt_pk_bf16_f32 v25, v6, v7
	v_cvt_pk_bf16_f32 v26, v12, v13
	v_cvt_pk_bf16_f32 v27, v14, v15
	s_waitcnt lgkmcnt(11)
	v_mfma_f32_16x16x32_bf16 v[32:35], v[156:159], v[20:23], 0
	s_waitcnt lgkmcnt(10)
	v_mfma_f32_16x16x32_bf16 v[32:35], v[160:163], v[16:19], v[32:35]
	s_waitcnt lgkmcnt(9)
	v_mfma_f32_16x16x32_bf16 v[32:35], v[190:193], v[28:31], v[32:35]
	s_waitcnt lgkmcnt(8)
	v_mfma_f32_16x16x32_bf16 v[32:35], v[194:197], v[24:27], v[32:35]
	v_add_u32_e32 v40, 0x1000, v137
	ds_read2_b64 v[138:141], v40 offset0:64 offset1:68
	ds_read2_b64 v[142:145], v40 offset0:72 offset1:76
	v_add_u32_e32 v40, 0x1800, v137
	ds_read2_b64 v[146:149], v40 offset0:96 offset1:100
	ds_read2_b64 v[150:153], v40 offset0:104 offset1:108
	s_waitcnt lgkmcnt(11)
	v_mfma_f32_16x16x32_bf16 v[36:39], v[164:167], v[20:23], 0
	s_waitcnt lgkmcnt(10)
	v_mfma_f32_16x16x32_bf16 v[36:39], v[168:171], v[16:19], v[36:39]
	s_waitcnt lgkmcnt(9)
	v_mfma_f32_16x16x32_bf16 v[36:39], v[198:201], v[28:31], v[36:39]
	s_waitcnt lgkmcnt(8)
	v_mfma_f32_16x16x32_bf16 v[36:39], v[202:205], v[24:27], v[36:39]
	v_mov_b32_e32 v41, v32
	v_mov_b32_e32 v42, v33
	v_mov_b32_e32 v43, v34
	v_mov_b32_e32 v44, v35
	s_waitcnt lgkmcnt(7)
	v_mfma_f32_16x16x32_bf16 v[32:35], v[172:175], v[20:23], 0
	s_waitcnt lgkmcnt(6)
	v_mfma_f32_16x16x32_bf16 v[32:35], v[176:179], v[16:19], v[32:35]
	s_waitcnt lgkmcnt(3)
	v_mfma_f32_16x16x32_bf16 v[32:35], v[138:141], v[28:31], v[32:35]
	s_waitcnt lgkmcnt(2)
	v_mfma_f32_16x16x32_bf16 v[32:35], v[142:145], v[24:27], v[32:35]
	v_mov_b32_e32 v45, v36
	v_mov_b32_e32 v46, v37
	v_mov_b32_e32 v47, v38
	v_mov_b32_e32 v56, v39
	ds_read_b128 v[156:159], v82 offset:55296
	ds_read_b128 v[160:163], v82 offset:55360
	ds_read_b128 v[164:167], v82 offset:55424
	ds_read_b128 v[168:171], v82 offset:55488
	ds_read_b128 v[190:193], v136 offset:18432
	ds_read_b128 v[194:197], v136 offset:18496
	ds_read_b128 v[198:201], v136 offset:20736
	ds_read_b128 v[202:205], v136 offset:20800
	v_mfma_f32_16x16x32_bf16 v[36:39], v[180:183], v[20:23], 0
	v_mfma_f32_16x16x32_bf16 v[36:39], v[184:187], v[16:19], v[36:39]
	s_waitcnt lgkmcnt(9)
	v_mfma_f32_16x16x32_bf16 v[36:39], v[146:149], v[28:31], v[36:39]
	s_waitcnt lgkmcnt(8)
	v_mfma_f32_16x16x32_bf16 v[36:39], v[150:153], v[24:27], v[36:39]
	ds_read_b128 v[172:175], v136 offset:23040
	ds_read_b128 v[176:179], v136 offset:23104
	ds_read_b128 v[180:183], v136 offset:25344
	ds_read_b128 v[184:187], v136 offset:25408
	s_waitcnt lgkmcnt(8)
	v_pk_mul_f32 v[8:9], v[8:9], v[156:157]
	v_pk_mul_f32 v[10:11], v[10:11], v[158:159]
	v_pk_mul_f32 v[0:1], v[0:1], v[160:161]
	v_pk_mul_f32 v[2:3], v[2:3], v[162:163]
	v_pk_mul_f32 v[4:5], v[4:5], v[164:165]
	v_pk_mul_f32 v[6:7], v[6:7], v[166:167]
	v_pk_mul_f32 v[12:13], v[12:13], v[168:169]
	v_pk_mul_f32 v[14:15], v[14:15], v[170:171]
	s_waitcnt lgkmcnt(7)
	v_mfma_f32_16x16x32_bf16 v[8:11], v[190:193], v[20:23], v[8:11]
	s_waitcnt lgkmcnt(6)
	v_mfma_f32_16x16x32_bf16 v[8:11], v[194:197], v[16:19], v[8:11]
	s_waitcnt lgkmcnt(5)
	v_mfma_f32_16x16x32_bf16 v[0:3], v[198:201], v[20:23], v[0:3]
	s_waitcnt lgkmcnt(4)
	v_mfma_f32_16x16x32_bf16 v[0:3], v[202:205], v[16:19], v[0:3]
	s_waitcnt lgkmcnt(3)
	v_mfma_f32_16x16x32_bf16 v[4:7], v[172:175], v[20:23], v[4:7]
	s_waitcnt lgkmcnt(2)
	v_mfma_f32_16x16x32_bf16 v[4:7], v[176:179], v[16:19], v[4:7]
	s_waitcnt lgkmcnt(1)
	v_mfma_f32_16x16x32_bf16 v[12:15], v[180:183], v[20:23], v[12:15]
	s_waitcnt lgkmcnt(0)
	v_mfma_f32_16x16x32_bf16 v[12:15], v[184:187], v[16:19], v[12:15]
	s_nop 7
	s_nop 3
	s_cmp_eq_u32 s51, 1
	s_cbranch_scc1 .Lp2f_sv1
	s_cmp_eq_u32 s51, 2
	s_cbranch_scc1 .Lp2f_sv2
	s_cmp_eq_u32 s51, 3
	s_cbranch_scc1 .Lp2f_sv3
	v_mov_b32_e32 v48, v41
	v_mov_b32_e32 v49, v42
	v_mov_b32_e32 v50, v43
	v_mov_b32_e32 v51, v44
	v_mov_b32_e32 v52, v45
	v_mov_b32_e32 v53, v46
	v_mov_b32_e32 v54, v47
	v_mov_b32_e32 v55, v56
	v_mov_b32_e32 v57, v32
	v_mov_b32_e32 v58, v33
	v_mov_b32_e32 v59, v34
	v_mov_b32_e32 v60, v35
	v_mov_b32_e32 v61, v36
	v_mov_b32_e32 v62, v37
	v_mov_b32_e32 v63, v38
	v_mov_b32_e32 v65, v39
	s_branch .Lp2f_svdone
.Lp2f_sv1:
	v_mov_b32_e32 v66, v41
	v_mov_b32_e32 v67, v42
	v_mov_b32_e32 v68, v43
	v_mov_b32_e32 v69, v44
	v_mov_b32_e32 v70, v45
	v_mov_b32_e32 v71, v46
	v_mov_b32_e32 v72, v47
	v_mov_b32_e32 v73, v56
	v_mov_b32_e32 v74, v32
	v_mov_b32_e32 v75, v33
	v_mov_b32_e32 v76, v34
	v_mov_b32_e32 v77, v35
	v_mov_b32_e32 v78, v36
	v_mov_b32_e32 v79, v37
	v_mov_b32_e32 v92, v38
	v_mov_b32_e32 v93, v39
	s_branch .Lp2f_svdone
.Lp2f_sv2:
	v_mov_b32_e32 v94, v41
	v_mov_b32_e32 v95, v42
	v_mov_b32_e32 v96, v43
	v_mov_b32_e32 v97, v44
	v_mov_b32_e32 v98, v45
	v_mov_b32_e32 v99, v46
	v_mov_b32_e32 v100, v47
	v_mov_b32_e32 v101, v56
	v_mov_b32_e32 v102, v32
	v_mov_b32_e32 v103, v33
	v_mov_b32_e32 v104, v34
	v_mov_b32_e32 v105, v35
	v_mov_b32_e32 v106, v36
	v_mov_b32_e32 v107, v37
	v_mov_b32_e32 v222, v38
	v_mov_b32_e32 v223, v39
	s_branch .Lp2f_svdone
.Lp2f_sv3:
	v_mov_b32_e32 v224, v41
	v_mov_b32_e32 v225, v42
	v_mov_b32_e32 v226, v43
	v_mov_b32_e32 v227, v44
	v_mov_b32_e32 v228, v45
	v_mov_b32_e32 v229, v46
	v_mov_b32_e32 v230, v47
	v_mov_b32_e32 v231, v56
	v_mov_b32_e32 v232, v32
	v_mov_b32_e32 v233, v33
	v_mov_b32_e32 v234, v34
	v_mov_b32_e32 v235, v35
	v_mov_b32_e32 v236, v36
	v_mov_b32_e32 v237, v37
	v_mov_b32_e32 v238, v38
	v_mov_b32_e32 v239, v39
.Lp2f_svdone:
	s_add_i32 s51, s51, 1
	s_add_i32 s64, s64, -1
	s_cmp_lg_u32 s51, 4
	s_waitcnt lgkmcnt(0)
	s_barrier
	s_cbranch_scc0 .LBB0_433
